# dattn interior loop: rare rescale block moved out of line and loop top restructured (one taken branch per tile instead of three), loop head 64-byte aligned
# speedup vs baseline: 1.0187x; 1.0047x over previous
.LBB0_1095:
	v_max_f32_e32 v2, v132, v132
	v_max_f32_e32 v0, v0, v0
	v_max_f32_e32 v0, v0, v2
	v_sub_f32_e32 v139, v76, v0
	v_sub_f32_e32 v140, v77, v0
	v_sub_f32_e32 v141, v78, v0
	v_sub_f32_e32 v149, v94, v0
	v_sub_f32_e32 v94, v79, v0
	v_mov_b64_e32 v[78:79], s[6:7]
	v_mov_b64_e32 v[76:77], s[4:5]
	v_sub_f32_e32 v69, v69, v0
	v_sub_f32_e32 v68, v68, v0
	v_add_f32_e32 v175, 0, v0
	v_sub_f32_e32 v2, v84, v0
	v_sub_f32_e32 v132, v85, v0
	v_sub_f32_e32 v133, v86, v0
	v_sub_f32_e32 v134, v87, v0
	v_sub_f32_e32 v135, v88, v0
	v_sub_f32_e32 v136, v89, v0
	v_sub_f32_e32 v137, v90, v0
	v_sub_f32_e32 v138, v91, v0
	v_sub_f32_e32 v92, v92, v0
	v_sub_f32_e32 v148, v93, v0
	v_sub_f32_e32 v150, v95, v0
	v_sub_f32_e32 v142, v80, v0
	v_sub_f32_e32 v151, v96, v0
	v_sub_f32_e32 v96, v81, v0
	v_sub_f32_e32 v152, v97, v0
	v_sub_f32_e32 v143, v82, v0
	v_sub_f32_e32 v153, v98, v0
	v_sub_f32_e32 v98, v83, v0
	v_sub_f32_e32 v154, v99, v0
	v_mfma_f32_32x32x16_bf16 v[52:67], v[100:103], v[76:79], v[52:67]
	v_sub_f32_e32 v75, v75, v0
	v_sub_f32_e32 v74, v74, v0
	v_sub_f32_e32 v3, v73, v0
	v_exp_f32_e32 v99, v68
	v_exp_f32_e32 v100, v69
	v_sub_f32_e32 v68, v72, v0
	v_sub_f32_e32 v69, v71, v0
	v_sub_f32_e32 v0, v70, v0
	v_exp_f32_e32 v0, v0
	v_exp_f32_e32 v102, v69
	v_add_f32_e32 v70, v99, v100
	v_mfma_f32_32x32x16_bf16 v[36:51], v[112:115], v[76:79], v[36:51]
	v_exp_f32_e32 v112, v68
	v_add_f32_e32 v68, v0, v102
	v_exp_f32_e32 v2, v2
	v_cvt_pk_bf16_f32 v145, v0, v102
	v_exp_f32_e32 v0, v134
	v_exp_f32_e32 v95, v139
	v_exp_f32_e32 v97, v140
	v_mfma_f32_32x32x16_bf16 v[20:35], v[108:111], v[76:79], v[20:35]
	v_exp_f32_e32 v108, v3
	v_add_f32_e32 v3, 0, v70
	v_add_f32_e32 v3, v68, v3
	ds_read_b64_tr_b16 v[68:69], v192 offset:34816
	ds_read_b64_tr_b16 v[70:71], v192 offset:35328
	v_add_f32_e32 v72, v112, v108
	v_add_f32_e32 v3, v72, v3
	v_exp_f32_e32 v101, v94
	v_mfma_f32_32x32x16_bf16 v[4:19], v[104:107], v[76:79], v[4:19]
	v_exp_f32_e32 v104, v74
	v_exp_f32_e32 v106, v75
	ds_read_b64_tr_b16 v[72:73], v192 offset:38912
	ds_read_b64_tr_b16 v[74:75], v192 offset:39424
	ds_read_b64_tr_b16 v[80:81], v192 offset:35840
	ds_read_b64_tr_b16 v[82:83], v192 offset:36352
	v_exp_f32_e32 v105, v96
	v_exp_f32_e32 v94, v92
	v_add_f32_e32 v93, v104, v106
	v_cvt_pk_bf16_f32 v147, v104, v106
	s_waitcnt lgkmcnt(4)
	v_mfma_f32_32x32x16_bf16 v[52:67], v[68:71], v[76:79], v[52:67]
	ds_read_b64_tr_b16 v[68:69], v192 offset:43008
	ds_read_b64_tr_b16 v[70:71], v192 offset:43520
	ds_read_b64_tr_b16 v[84:85], v192 offset:47104
	ds_read_b64_tr_b16 v[86:87], v192 offset:47616
	ds_read_b64_tr_b16 v[88:89], v192 offset:39936
	ds_read_b64_tr_b16 v[90:91], v192 offset:40448
	v_exp_f32_e32 v106, v136
	v_exp_f32_e32 v96, v148
	v_cvt_pk_bf16_f32 v144, v99, v100
	v_exp_f32_e32 v99, v141
	v_exp_f32_e32 v100, v150
	v_exp_f32_e32 v103, v142
	s_waitcnt lgkmcnt(2)
	v_mfma_f32_32x32x16_bf16 v[4:19], v[84:87], v[76:79], v[4:19]
	v_exp_f32_e32 v84, v132
	v_exp_f32_e32 v86, v133
	v_exp_f32_e32 v85, v98
	v_exp_f32_e32 v98, v149
	v_add_f32_e32 v87, v2, v84
	v_exp_f32_e32 v102, v151
	v_exp_f32_e32 v104, v152
	v_mfma_f32_32x32x16_bf16 v[36:51], v[72:75], v[76:79], v[36:51]
	ds_read_b64_tr_b16 v[72:73], v192 offset:44032
	ds_read_b64_tr_b16 v[74:75], v192 offset:44544
	v_exp_f32_e32 v107, v143
	v_cvt_pk_bf16_f32 v136, v2, v84
	v_exp_f32_e32 v84, v154
	v_cvt_pk_bf16_f32 v146, v112, v108
	v_cvt_pk_bf16_f32 v140, v95, v97
	v_cvt_pk_bf16_f32 v141, v99, v101
	v_mfma_f32_32x32x16_bf16 v[20:35], v[68:71], v[76:79], v[20:35]
	ds_read_b64_tr_b16 v[68:69], v192 offset:48128
	ds_read_b64_tr_b16 v[70:71], v192 offset:48640
	v_cvt_pk_bf16_f32 v142, v103, v105
	v_cvt_pk_bf16_f32 v143, v107, v85
	v_cvt_pk_bf16_f32 v132, v94, v96
	v_cvt_pk_bf16_f32 v133, v98, v100
	v_cvt_pk_bf16_f32 v134, v102, v104
	s_cmp_eq_u32 s25, 1
	v_mfma_f32_32x32x16_bf16 v[52:67], v[80:83], v[76:79], v[52:67]
	v_add_f32_e64 v80, v86, v0
	v_add_f32_e64 v81, v87, v1
	v_exp_f32_e32 v87, v135
	v_pk_add_f32 v[80:81], v[80:81], v[80:81] op_sel_hi:[0,1]
	v_exp_f32_e32 v82, v137
	v_exp_f32_e32 v80, v138
	v_add_f32_e32 v83, v87, v106
	v_cvt_pk_bf16_f32 v138, v87, v106
	s_waitcnt lgkmcnt(4)
	v_mfma_f32_32x32x16_bf16 v[36:51], v[88:91], v[76:79], v[36:51]
	v_add_f32_e64 v88, v82, v80
	v_add_f32_e64 v89, v83, v81
	v_exp_f32_e32 v106, v153
	v_mov_b32_e32 v92, v88
	v_mov_b32_e32 v2, v89
	v_pk_add_f32 v[2:3], v[92:93], v[2:3]
	v_cvt_pk_bf16_f32 v137, v86, v0
	v_cvt_pk_bf16_f32 v139, v82, v80
	s_waitcnt lgkmcnt(2)
	v_mfma_f32_32x32x16_bf16 v[20:35], v[72:75], v[76:79], v[20:35]
	v_cvt_pk_bf16_f32 v135, v106, v84
	s_waitcnt lgkmcnt(0)
	v_mfma_f32_32x32x16_bf16 v[4:19], v[68:71], v[76:79], v[4:19]
	v_add_f32_e64 v68, v94, v96
	v_add_f32_e64 v69, v95, v97
	v_add_f32_e64 v2, v68, v2
	v_add_f32_e64 v3, v69, v3
	v_add_f32_e64 v68, v98, v100
	v_add_f32_e64 v69, v99, v101
	v_pk_add_f32 v[2:3], v[68:69], v[2:3]
	v_pk_add_f32 v[68:69], v[102:103], v[104:105]
	s_nop 0
	v_pk_add_f32 v[2:3], v[68:69], v[2:3]
	v_pk_add_f32 v[68:69], v[106:107], v[84:85]
	s_nop 0
	v_pk_add_f32 v[2:3], v[68:69], v[2:3]
	s_nop 0
	v_add_f32_e32 v0, v2, v3
	v_add_f32_e32 v173, 0, v0
	s_cbranch_scc1 .LBB0_1106
	s_and_b32 s6, s41, 7
	s_mul_i32 s5, s24, 0x3000000
	s_lshl_b32 s6, s6, 8
	s_or_b32 s5, s5, s6
	s_mul_hi_i32 s3, s24, 0x3000000
	s_add_u32 s6, s5, s26
	s_addc_u32 s7, s3, 0
	v_mov_b32_e32 v181, v1
	v_xor_b32_e32 v100, 0x80000000, v175
	v_lshl_add_u64 v[2:3], s[6:7], 0, v[180:181]
	s_mov_b32 s64, 1
	v_lshl_add_u64 v[182:183], v[168:169], 0, v[2:3]
	v_lshl_add_u64 v[184:185], v[178:179], 0, s[22:23]
	s_mov_b32 s3, 0x10000
	s_movk_i32 s5, 0x2000
	v_mov_b32_e32 v101, v100
	v_mov_b32_e32 v102, v100
	v_mov_b32_e32 v103, v100
	v_mov_b32_e32 v104, v100
	v_mov_b32_e32 v105, v100
	v_mov_b32_e32 v106, v100
	v_mov_b32_e32 v107, v100
	v_mov_b32_e32 v108, v100
	v_mov_b32_e32 v109, v100
	v_mov_b32_e32 v110, v100
	v_mov_b32_e32 v111, v100
	v_mov_b32_e32 v112, v100
	v_mov_b32_e32 v113, v100
	v_mov_b32_e32 v114, v100
	v_mov_b32_e32 v115, v100
	s_add_i32 s27, s64, 1
	s_cmp_ge_i32 s27, s54
	s_cbranch_scc0 .Ldattn_top_bar
.LBB0_1098:
	s_waitcnt vmcnt(0) lgkmcnt(0)
	s_barrier
	s_branch .LBB0_1101
.Ldattn_rare:
	s_waitcnt lgkmcnt(6)
	v_mfma_f32_32x32x16_bf16 v[52:67], v[160:163], v[144:147], v[52:67]
	ds_read_b64_tr_b16 v[100:101], v177 offset:33792
	ds_read_b64_tr_b16 v[102:103], v177 offset:34304
	ds_read_b64_tr_b16 v[162:163], v177 offset:33280
	v_max_f32_e32 v0, v0, v0
	v_max_f32_e32 v2, 0, v0
	v_exp_f32_e64 v0, -v2
	v_add_f32_e32 v175, v175, v2
	v_sub_f32_e32 v99, v99, v2
	v_sub_f32_e32 v98, v98, v2
	s_waitcnt lgkmcnt(7)
	v_mfma_f32_32x32x16_bf16 v[36:51], v[156:159], v[144:147], v[36:51]
	v_sub_f32_e32 v97, v97, v2
	v_sub_f32_e32 v96, v96, v2
	v_sub_f32_e32 v95, v95, v2
	v_sub_f32_e32 v94, v94, v2
	v_sub_f32_e32 v93, v93, v2
	v_sub_f32_e32 v92, v92, v2
	v_sub_f32_e32 v91, v91, v2
	s_waitcnt lgkmcnt(5)
	v_mfma_f32_32x32x16_bf16 v[20:35], v[152:155], v[144:147], v[20:35]
	v_sub_f32_e32 v90, v90, v2
	v_sub_f32_e32 v89, v89, v2
	v_sub_f32_e32 v88, v88, v2
	v_sub_f32_e32 v87, v87, v2
	v_sub_f32_e32 v86, v86, v2
	v_sub_f32_e32 v85, v85, v2
	v_sub_f32_e32 v84, v84, v2
	s_waitcnt lgkmcnt(1)
	v_mfma_f32_32x32x16_bf16 v[52:67], v[100:103], v[140:143], v[52:67]
	ds_read_b64_tr_b16 v[100:101], v177 offset:37888
	ds_read_b64_tr_b16 v[102:103], v177 offset:38400
	ds_read_b64_tr_b16 v[158:159], v177 offset:37376
	v_sub_f32_e32 v83, v83, v2
	v_sub_f32_e32 v82, v82, v2
	v_sub_f32_e32 v81, v81, v2
	v_sub_f32_e32 v80, v80, v2
	v_sub_f32_e32 v79, v79, v2
	v_sub_f32_e32 v78, v78, v2
	v_mfma_f32_32x32x16_bf16 v[4:19], v[148:151], v[144:147], v[4:19]
	v_sub_f32_e32 v77, v77, v2
	v_sub_f32_e32 v76, v76, v2
	v_sub_f32_e32 v75, v75, v2
	v_sub_f32_e32 v74, v74, v2
	v_sub_f32_e32 v73, v73, v2
	v_sub_f32_e32 v72, v72, v2
	v_sub_f32_e32 v71, v71, v2
	s_waitcnt lgkmcnt(1)
	v_mfma_f32_32x32x16_bf16 v[36:51], v[100:103], v[140:143], v[36:51]
	ds_read_b64_tr_b16 v[100:101], v177 offset:41984
	ds_read_b64_tr_b16 v[102:103], v177 offset:42496
	ds_read_b64_tr_b16 v[154:155], v177 offset:41472
	v_sub_f32_e32 v70, v70, v2
	v_sub_f32_e32 v69, v69, v2
	v_sub_f32_e32 v68, v68, v2
	v_mov_b32_e32 v2, v1
	v_mov_b32_e32 v3, v1
	v_mul_f32_e32 v173, v173, v0
	s_waitcnt lgkmcnt(1)
	v_mfma_f32_32x32x16_bf16 v[20:35], v[100:103], v[140:143], v[20:35]
	ds_read_b64_tr_b16 v[100:101], v177 offset:46080
	ds_read_b64_tr_b16 v[102:103], v177 offset:46592
	ds_read_b64_tr_b16 v[150:151], v177 offset:45568
	s_waitcnt lgkmcnt(1)
	v_mfma_f32_32x32x16_bf16 v[4:19], v[100:103], v[140:143], v[4:19]
	ds_read_b64_tr_b16 v[100:101], v177 offset:34816
	ds_read_b64_tr_b16 v[102:103], v177 offset:35328
	ds_read_b64_tr_b16 v[104:105], v177 offset:35840
	ds_read_b64_tr_b16 v[106:107], v177 offset:36352
	s_waitcnt lgkmcnt(2)
	v_mfma_f32_32x32x16_bf16 v[52:67], v[100:103], v[136:139], v[52:67]
	ds_read_b64_tr_b16 v[100:101], v177 offset:38912
	ds_read_b64_tr_b16 v[102:103], v177 offset:39424
	ds_read_b64_tr_b16 v[108:109], v177 offset:39936
	ds_read_b64_tr_b16 v[110:111], v177 offset:40448
	s_waitcnt lgkmcnt(2)
	v_mfma_f32_32x32x16_bf16 v[36:51], v[100:103], v[136:139], v[36:51]
	ds_read_b64_tr_b16 v[100:101], v177 offset:43008
	ds_read_b64_tr_b16 v[102:103], v177 offset:43520
	ds_read_b64_tr_b16 v[112:113], v177 offset:44032
	ds_read_b64_tr_b16 v[114:115], v177 offset:44544
	ds_read_b64_tr_b16 v[160:161], v177 offset:32768
	ds_read_b64_tr_b16 v[156:157], v177 offset:36864
	ds_read_b64_tr_b16 v[152:153], v177 offset:40960
	ds_read_b64_tr_b16 v[148:149], v177 offset:45056
	s_waitcnt lgkmcnt(6)
	v_mfma_f32_32x32x16_bf16 v[20:35], v[100:103], v[136:139], v[20:35]
	v_mfma_f32_32x32x16_bf16 v[52:67], v[104:107], v[132:135], v[52:67]
	ds_read_b64_tr_b16 v[100:101], v177 offset:47104
	ds_read_b64_tr_b16 v[102:103], v177 offset:47616
	ds_read_b64_tr_b16 v[104:105], v177 offset:48128
	ds_read_b64_tr_b16 v[106:107], v177 offset:48640
	s_waitcnt lgkmcnt(2)
	v_mfma_f32_32x32x16_bf16 v[4:19], v[100:103], v[136:139], v[4:19]
	s_nop 5
	v_mul_f32_e64 v66, v0, v66
	v_mul_f32_e64 v67, v0, v67
	v_mul_f32_e64 v64, v0, v64
	v_mul_f32_e64 v65, v0, v65
	v_mul_f32_e64 v62, v0, v62
	v_mul_f32_e64 v63, v0, v63
	v_pk_mul_f32 v[60:61], v[0:1], v[60:61] op_sel_hi:[0,1]
	v_pk_mul_f32 v[58:59], v[0:1], v[58:59] op_sel_hi:[0,1]
	v_pk_mul_f32 v[56:57], v[0:1], v[56:57] op_sel_hi:[0,1]
	v_pk_mul_f32 v[54:55], v[0:1], v[54:55] op_sel_hi:[0,1]
	v_mfma_f32_32x32x16_bf16 v[36:51], v[108:111], v[132:135], v[36:51]
	v_mul_f32_e64 v52, v0, v52
	v_mul_f32_e64 v53, v0, v53
	v_xor_b32_e32 v100, 0x80000000, v175
	v_mov_b32_e32 v101, v100
	v_mov_b32_e32 v102, v100
	v_mov_b32_e32 v103, v100
	v_mov_b32_e32 v108, v100
	v_mov_b32_e32 v109, v100
	v_mfma_f32_32x32x16_bf16 v[20:35], v[112:115], v[132:135], v[20:35]
	s_nop 2
	v_mul_f32_e64 v50, v0, v50
	v_mul_f32_e64 v51, v0, v51
	v_mul_f32_e64 v48, v0, v48
	v_mul_f32_e64 v49, v0, v49
	v_mul_f32_e64 v46, v0, v46
	v_mul_f32_e64 v47, v0, v47
	v_pk_mul_f32 v[44:45], v[0:1], v[44:45] op_sel_hi:[0,1]
	v_pk_mul_f32 v[42:43], v[0:1], v[42:43] op_sel_hi:[0,1]
	v_pk_mul_f32 v[40:41], v[0:1], v[40:41] op_sel_hi:[0,1]
	v_pk_mul_f32 v[38:39], v[0:1], v[38:39] op_sel_hi:[0,1]
	s_waitcnt lgkmcnt(0)
	v_mfma_f32_32x32x16_bf16 v[4:19], v[104:107], v[132:135], v[4:19]
	v_mul_f32_e64 v36, v0, v36
	v_mul_f32_e64 v37, v0, v37
	v_mul_f32_e64 v34, v0, v34
	v_mul_f32_e64 v35, v0, v35
	v_mul_f32_e64 v32, v0, v32
	v_mul_f32_e64 v33, v0, v33
	v_pk_mul_f32 v[30:31], v[0:1], v[30:31] op_sel_hi:[0,1]
	v_pk_mul_f32 v[28:29], v[0:1], v[28:29] op_sel_hi:[0,1]
	v_pk_mul_f32 v[26:27], v[0:1], v[26:27] op_sel_hi:[0,1]
	v_pk_mul_f32 v[24:25], v[0:1], v[24:25] op_sel_hi:[0,1]
	v_pk_mul_f32 v[22:23], v[0:1], v[22:23] op_sel_hi:[0,1]
	v_pk_mul_f32 v[20:21], v[0:1], v[20:21] op_sel_hi:[0,1]
	v_pk_mul_f32 v[18:19], v[0:1], v[18:19] op_sel_hi:[0,1]
	v_pk_mul_f32 v[16:17], v[0:1], v[16:17] op_sel_hi:[0,1]
	v_pk_mul_f32 v[14:15], v[0:1], v[14:15] op_sel_hi:[0,1]
	v_pk_mul_f32 v[12:13], v[0:1], v[12:13] op_sel_hi:[0,1]
	v_pk_mul_f32 v[10:11], v[0:1], v[10:11] op_sel_hi:[0,1]
	v_pk_mul_f32 v[8:9], v[0:1], v[8:9] op_sel_hi:[0,1]
	v_pk_mul_f32 v[6:7], v[0:1], v[6:7] op_sel_hi:[0,1]
	v_pk_mul_f32 v[4:5], v[0:1], v[4:5] op_sel_hi:[0,1]
	v_mov_b32_e32 v0, v1
	v_mov_b64_e32 v[146:147], v[2:3]
	v_mov_b64_e32 v[142:143], v[2:3]
	v_mov_b64_e32 v[138:139], v[2:3]
	v_mov_b64_e32 v[134:135], v[2:3]
	v_mov_b64_e32 v[144:145], v[0:1]
	v_mov_b64_e32 v[140:141], v[0:1]
	v_mov_b64_e32 v[136:137], v[0:1]
	v_mov_b64_e32 v[132:133], v[0:1]
	v_mov_b32_e32 v104, v100
	v_mov_b32_e32 v105, v100
	v_mov_b32_e32 v106, v100
	v_mov_b32_e32 v107, v100
	v_mov_b32_e32 v110, v100
	v_mov_b32_e32 v111, v100
	v_mov_b32_e32 v112, v100
	v_mov_b32_e32 v113, v100
	v_mov_b32_e32 v114, v100
	v_mov_b32_e32 v115, v100
	s_branch .LBB0_1103
	.p2alignl 6, 3212836864
.LBB0_1097:
	s_mov_b32 s64, s27
	s_add_i32 s27, s64, 1
	s_cmp_ge_i32 s27, s54
	s_cbranch_scc1 .LBB0_1098

.LBB0_1101:
	s_and_b32 s6, s5, 0x6000
	v_add_u32_e32 v0, s6, v189
	ds_read_b128 v[164:167], v0
	ds_read_b128 v[208:211], v0 offset:512
	ds_read_b128 v[212:215], v0 offset:2560
	ds_read_b128 v[216:219], v0 offset:2048
	ds_read_b128 v[220:223], v0 offset:4608
	ds_read_b128 v[224:227], v0 offset:4096
	ds_read_b128 v[200:203], v0 offset:6656
	ds_read_b128 v[228:231], v0 offset:6144
	s_and_b32 s6, s3, 0xc000
	v_add_u32_e32 v177, s6, v192
	s_waitcnt lgkmcnt(7)
	v_mfma_f32_32x32x16_bf16 v[84:99], v[164:167], v[128:131], v[100:115]
	s_waitcnt lgkmcnt(6)
	v_mfma_f32_32x32x16_bf16 v[68:83], v[208:211], v[128:131], v[100:115]
	s_waitcnt lgkmcnt(5)
	v_mfma_f32_32x32x16_bf16 v[68:83], v[212:215], v[124:127], v[68:83]
	s_waitcnt lgkmcnt(4)
	v_mfma_f32_32x32x16_bf16 v[84:99], v[216:219], v[124:127], v[84:99]
	s_waitcnt lgkmcnt(3)
	v_mfma_f32_32x32x16_bf16 v[68:83], v[220:223], v[120:123], v[68:83]
	s_waitcnt lgkmcnt(2)
	v_mfma_f32_32x32x16_bf16 v[84:99], v[224:227], v[120:123], v[84:99]
	s_waitcnt lgkmcnt(1)
	v_mfma_f32_32x32x16_bf16 v[68:83], v[200:203], v[116:119], v[68:83]
	s_waitcnt lgkmcnt(0)
	v_mfma_f32_32x32x16_bf16 v[84:99], v[228:231], v[116:119], v[84:99]
	ds_read_b64_tr_b16 v[160:161], v177 offset:32768
	ds_read_b64_tr_b16 v[162:163], v177 offset:33280
	ds_read_b64_tr_b16 v[156:157], v177 offset:36864
	ds_read_b64_tr_b16 v[158:159], v177 offset:37376
	ds_read_b64_tr_b16 v[152:153], v177 offset:40960
	ds_read_b64_tr_b16 v[154:155], v177 offset:41472
	ds_read_b64_tr_b16 v[148:149], v177 offset:45056
	ds_read_b64_tr_b16 v[150:151], v177 offset:45568
	s_nop 2
	v_max_i32_e32 v2, v68, v69
	v_max3_i32 v2, v2, v70, v71
	v_max3_i32 v2, v2, v72, v73
	v_max3_i32 v2, v2, v74, v75
	v_max3_i32 v2, v2, v76, v77
	v_max3_i32 v2, v2, v78, v79
	v_max3_i32 v2, v2, v80, v81
	v_max3_i32 v0, v84, v85, v86
	v_max3_i32 v0, v0, v87, v88
	v_max3_i32 v0, v0, v89, v90
	v_max3_i32 v0, v0, v91, v92
	v_max3_i32 v0, v0, v93, v94
	v_max3_i32 v0, v0, v95, v96
	v_max3_i32 v0, v0, v97, v98
	v_max3_i32 v2, v2, v82, v83
	v_max3_i32 v0, v0, v99, v2
	v_mov_b32_e32 v2, v0
	s_nop 1
	v_permlane32_swap_b32_e32 v0, v2
	v_max_f32_e32 v2, v2, v2
	v_max_f32_e32 v0, v0, v0
	v_max_f32_e32 v0, v0, v2
	v_cmp_lt_f32_e32 vcc, s38, v0
	s_cbranch_vccnz .Ldattn_rare

.LBB0_1105:
	v_exp_f32_e32 v95, v95
	v_exp_f32_e32 v96, v96
	v_add_f32_e32 v234, v88, v89
	v_add_f32_e32 v235, v90, v91
	v_cvt_pk_bf16_f32 v144, v84, v85
	v_cvt_pk_bf16_f32 v145, v86, v87
	s_waitcnt lgkmcnt(6)
	v_mfma_f32_32x32x16_bf16 v[52:67], v[164:167], v[140:143], v[52:67]
	v_exp_f32_e32 v97, v97
	v_exp_f32_e32 v98, v98
	v_cvt_pk_bf16_f32 v146, v88, v89
	v_cvt_pk_bf16_f32 v147, v90, v91
	v_add_f32_e32 v232, v92, v232
	v_add_f32_e32 v233, v93, v233
	ds_read_b64_tr_b16 v[84:85], v177 offset:34816
	ds_read_b64_tr_b16 v[86:87], v177 offset:35328
	s_waitcnt lgkmcnt(6)
	v_mfma_f32_32x32x16_bf16 v[36:51], v[160:163], v[140:143], v[36:51]
	v_exp_f32_e32 v99, v99
	v_exp_f32_e32 v68, v68
	v_add_f32_e32 v234, v94, v234
	v_add_f32_e32 v235, v95, v235
	v_add_f32_e32 v232, v96, v232
	s_waitcnt lgkmcnt(4)
	v_mfma_f32_32x32x16_bf16 v[20:35], v[156:159], v[140:143], v[20:35]
	v_exp_f32_e32 v69, v69
	v_exp_f32_e32 v70, v70
	v_add_f32_e32 v233, v97, v233
	v_add_f32_e32 v234, v98, v234
	v_add_f32_e32 v235, v99, v235
	s_waitcnt lgkmcnt(2)
	v_mfma_f32_32x32x16_bf16 v[4:19], v[152:155], v[140:143], v[4:19]
	v_cvt_pk_bf16_f32 v140, v92, v93
	v_cvt_pk_bf16_f32 v141, v94, v95
	v_cvt_pk_bf16_f32 v142, v96, v97
	v_cvt_pk_bf16_f32 v143, v98, v99
	v_exp_f32_e32 v71, v71
	v_exp_f32_e32 v72, v72
	ds_read_b64_tr_b16 v[88:89], v177 offset:35840
	ds_read_b64_tr_b16 v[90:91], v177 offset:36352
	s_waitcnt lgkmcnt(2)
	v_mfma_f32_32x32x16_bf16 v[52:67], v[84:87], v[136:139], v[52:67]
	v_exp_f32_e32 v73, v73
	v_exp_f32_e32 v74, v74
	v_add_f32_e32 v232, v68, v232
	v_add_f32_e32 v233, v69, v233
	v_add_f32_e32 v234, v70, v234
	ds_read_b64_tr_b16 v[84:85], v177 offset:38912
	ds_read_b64_tr_b16 v[86:87], v177 offset:39424
	ds_read_b64_tr_b16 v[92:93], v177 offset:39936
	ds_read_b64_tr_b16 v[94:95], v177 offset:40448
	ds_read_b64_tr_b16 v[96:97], v177 offset:43008
	ds_read_b64_tr_b16 v[98:99], v177 offset:43520
	ds_read_b64_tr_b16 v[148:149], v177 offset:44032
	ds_read_b64_tr_b16 v[150:151], v177 offset:44544
	s_waitcnt lgkmcnt(6)
	v_mfma_f32_32x32x16_bf16 v[36:51], v[84:87], v[136:139], v[36:51]
	v_exp_f32_e32 v75, v75
	v_exp_f32_e32 v76, v76
	v_add_f32_e32 v235, v71, v235
	v_add_f32_e32 v232, v72, v232
	v_add_f32_e32 v233, v73, v233
	ds_read_b64_tr_b16 v[84:85], v177 offset:47104
	ds_read_b64_tr_b16 v[86:87], v177 offset:47616
	ds_read_b64_tr_b16 v[152:153], v177 offset:48128
	ds_read_b64_tr_b16 v[154:155], v177 offset:48640
	s_waitcnt lgkmcnt(6)
	v_mfma_f32_32x32x16_bf16 v[20:35], v[96:99], v[136:139], v[20:35]
	v_exp_f32_e32 v77, v77
	v_exp_f32_e32 v78, v78
	v_add_f32_e32 v234, v74, v234
	v_add_f32_e32 v235, v75, v235
	v_add_f32_e32 v232, v76, v232
	s_addk_i32 s3, 0x4000
	s_addk_i32 s5, 0x2000
	s_waitcnt lgkmcnt(2)
	v_mfma_f32_32x32x16_bf16 v[4:19], v[84:87], v[136:139], v[4:19]
	v_exp_f32_e32 v79, v79
	v_exp_f32_e32 v80, v80
	v_add_f32_e32 v233, v77, v233
	v_add_f32_e32 v234, v78, v234
	v_lshl_add_u64 v[182:183], v[182:183], 0, s[14:15]
	v_mfma_f32_32x32x16_bf16 v[52:67], v[88:91], v[132:135], v[52:67]
	v_cvt_pk_bf16_f32 v136, v68, v69
	v_cvt_pk_bf16_f32 v137, v70, v71
	v_cvt_pk_bf16_f32 v138, v72, v73
	v_cvt_pk_bf16_f32 v139, v74, v75
	v_exp_f32_e32 v81, v81
	v_add_f32_e32 v235, v79, v235
	v_mfma_f32_32x32x16_bf16 v[36:51], v[92:95], v[132:135], v[36:51]
	v_exp_f32_e32 v82, v82
	v_exp_f32_e32 v83, v83
	v_add_f32_e32 v232, v80, v232
	v_add_f32_e32 v233, v81, v233
	v_lshl_add_u64 v[184:185], v[184:185], 0, s[14:15]
	v_mfma_f32_32x32x16_bf16 v[20:35], v[148:151], v[132:135], v[20:35]
	v_add_f32_e32 v234, v82, v234
	v_add_f32_e32 v235, v83, v235
	v_add_f32_e32 v232, v233, v232
	v_add_f32_e32 v234, v235, v234
	v_add_f32_e32 v232, v234, v232
	v_add_f32_e32 v173, v173, v232
	s_cmp_lg_u32 s25, s27
	s_waitcnt lgkmcnt(0)
	v_mfma_f32_32x32x16_bf16 v[4:19], v[152:155], v[132:135], v[4:19]
	v_cvt_pk_bf16_f32 v132, v76, v77
	v_cvt_pk_bf16_f32 v133, v78, v79
	v_cvt_pk_bf16_f32 v134, v80, v81
	v_cvt_pk_bf16_f32 v135, v82, v83
	s_cbranch_scc1 .LBB0_1097
	s_nop 0
	s_nop 0
	s_nop 0
	s_nop 0
	s_nop 0
	s_nop 0
	s_nop 0
	s_nop 0
	s_nop 0
	s_nop 0
	s_nop 0
	s_nop 0
	s_nop 0
	s_nop 0
